# GDN scan: packed v_pk_mul_f32 state-decay multiplies between MFMAs split into scalar v_mul_f32 pairs
# baseline (speedup 1.0000x reference)
; DI bf16x8 tr2(const bf16_t* p0, const bf16_t* p1) { s16x4 a = trread(p0), b = trread(p1); return __builtin_shufflevector(a, b, 0, 1, 2, 3, 4, 5, 6, 7); }
; DI f32x4 mfma16(bf16x8 a, bf16x8 b, f32x4 c) { return __builtin_amdgcn_mfma_f32_16x16x32_bf16(a, b, c, 0, 0, 0); }
; DI void gdn_scan_item(const P& p, int item, unsigned char* smem) {
;     ...
; #pragma unroll
;         for (int j = 0; j < 2; ++j) {
;             const int dt = 2 * mt + j;
;             st[j] *= dec;
; #pragma unroll
;             for (int k2 = 0; k2 < 2; ++k2) {
;                 const bf16x8 ak = tr2(sKO + (32 * k2 + 8 * g + q4) * 136 + 16 * dt + 4 * p4, sKO + (32 * k2 + 8 * g + 4 + q4) * 136 + 16 * dt + 4 * p4);
;                 st[j] = mfma16(ak, Bv[k2], st[j]);
;             }
;         }
;         sBS[(nt * 4 + mt) * 64 + lane] = __builtin_bit_cast(u32x4, packacc(st[0], st[1]));
.LBB0_500:
	ds_read_b64_tr_b16 v[226:227], v187 offset:35904
	ds_read_b64_tr_b16 v[224:225], v187 offset:34816
	ds_read_b64_tr_b16 v[228:229], v187 offset:34848
	ds_read_b64_tr_b16 v[232:233], v193 offset:34848
	ds_read_b64_tr_b16 v[230:231], v187 offset:35936
	ds_read_b64_tr_b16 v[234:235], v187 offset:44640
	s_ashr_i32 s43, s42, 31
	s_lshl_b64 s[4:5], s[42:43], 10
	s_nop 2
	v_cvt_pk_bf16_f32 v112, v112, v113
	v_cvt_pk_bf16_f32 v113, v114, v115
	v_lshl_add_u64 v[114:115], v[126:127], 0, s[4:5]
	global_store_dwordx2 v[114:115], v[112:113], off
	ds_read_b64_tr_b16 v[114:115], v187 offset:44608
	ds_read_b64_tr_b16 v[112:113], v193 offset:34816
	v_mul_f32_e32 v98, v132, v98
	v_mul_f32_e32 v99, v132, v99
	v_mul_f32_e32 v96, v132, v96
	v_mul_f32_e32 v97, v132, v97
	v_mul_f32_e32 v102, v132, v102
	v_mul_f32_e32 v103, v132, v103
	v_mul_f32_e32 v100, v132, v100
	v_mul_f32_e32 v101, v132, v101
	s_waitcnt lgkmcnt(6)
	v_mfma_f32_16x16x32_bf16 v[96:99], v[224:227], v[108:111], v[96:99]
	s_waitcnt lgkmcnt(0)
	v_mfma_f32_16x16x32_bf16 v[96:99], v[112:115], v[104:107], v[96:99]
	s_mov_b64 s[4:5], 0x6000
	v_lshl_add_u64 v[142:143], v[142:143], 0, s[4:5]
	s_mov_b64 s[4:5], 0xc000
	v_mfma_f32_16x16x32_bf16 v[100:103], v[228:231], v[108:111], v[100:103]
	s_add_i32 s21, s21, 12
	s_addk_i32 s22, 0xc0
	s_addk_i32 s24, 0xff40
	v_mfma_f32_16x16x32_bf16 v[100:103], v[232:235], v[104:107], v[100:103]
	v_cvt_pk_bf16_f32 v104, v96, v97
	v_cvt_pk_bf16_f32 v105, v98, v99
	v_lshl_add_u64 v[144:145], v[144:145], 0, s[4:5]
	v_lshl_add_u64 v[146:147], v[146:147], 0, s[4:5]
	v_lshl_add_u64 v[148:149], v[148:149], 0, s[4:5]
	s_nop 2
	v_cvt_pk_bf16_f32 v106, v100, v101
	v_cvt_pk_bf16_f32 v107, v102, v103
	s_cmp_lt_u32 s26, 33
	s_mov_b32 s27, s26
	ds_write_b128 v156, v[104:107]
	s_waitcnt lgkmcnt(0)
	s_cbranch_scc0 .LBB0_640

; DI float lo16(unsigned u) { return __uint_as_float(u << 16); }
; DI void gdn_scan_item(const P& p, int item, unsigned char* smem) {
;     ...
;     auto step = [&](GdnRegs& R, int c) {
;         storel(R, c & 1);
;         __syncthreads();
;         loadr(R, c + 3);
;         const bf16_t* sW = (const bf16_t*)(smem + (c & 1) * BUFB); const bf16_t* sQI = sW + 64 * 136; const bf16_t* sKO = sQI + 64 * 136; const bf16_t* sAT = sKO + 64 * 136; const bf16_t* sU = sAT + 64 * 72;
;         const float dec = sdec[c];
;         bf16x8 Bs[4];
; #pragma unroll
;         for (int ks = 0; ks < 4; ++ks) Bs[ks] = __builtin_bit_cast(bf16x8, sBS[(nt * 4 + ks) * 64 + lane]);
;         {
;             f32x4 acc = (f32x4){0.f, 0.f, 0.f, 0.f};
; #pragma unroll
;             for (int ks = 0; ks < 4; ++ks) { const bf16_t* r0 = sW + (16 * mt + l15) * 136 + 32 * ks + 4 * g; acc = mfma16(Bs[ks], ld4x2(r0, r0 + 16), acc); }
;             {
;                 const u32x2 uu = *(const u32x2*)(sU + (16 * mt + l15) * 40 + 16 * nt + 4 * g);
;                 u32x2 vv; vv.x = pk2(lo16(uu.x) - acc[0], hi16(uu.x) - acc[1]); vv.y = pk2(lo16(uu.y) - acc[2], hi16(uu.y) - acc[3]);
;                 *(u32x2*)(sVN + (16 * mt + l15) * 40 + 16 * nt + 4 * g) = vv;
;             }
;         }
;         __syncthreads();
;         bf16x8 Bv[2];
; #pragma unroll
;         for (int k2 = 0; k2 < 2; ++k2) Bv[k2] = tr2(sVN + (32 * k2 + 8 * g + q4) * 40 + 16 * nt + 4 * p4, sVN + (32 * k2 + 8 * g + 4 + q4) * 40 + 16 * nt + 4 * p4);
;         {
;             f32x4 acc = (f32x4){0.f, 0.f, 0.f, 0.f};
; #pragma unroll
;             for (int ks = 0; ks < 4; ++ks) { const bf16_t* r0 = sQI + (16 * mt + l15) * 136 + 32 * ks + 4 * g; acc = mfma16(Bs[ks], ld4x2(r0, r0 + 16), acc); }
; #pragma unroll
;             for (int k2 = 0; k2 < 2; ++k2) acc = mfma16(Bv[k2], ld8(sAT + (16 * mt + l15) * 72 + 32 * k2 + 8 * g), acc);
;             bf16_t* ob = OG + (size_t)prow(b, dir, 64 * c) * 512 + 128 * h + 32 * cq;
;             u32x2 ov; ov.x = pk2(acc[0], acc[1]); ov.y = pk2(acc[2], acc[3]);
;             *(u32x2*)(ob + sgn * ((16 * mt + l15) * 512) + 16 * nt + 4 * g) = ov;
;         }
; #pragma unroll
;         for (int j = 0; j < 2; ++j) {
;             const int dt = 2 * mt + j;
;             st[j] *= dec;
; #pragma unroll
;             for (int k2 = 0; k2 < 2; ++k2) {
.LBB0_511:
	v_lshl_add_u32 v134, v125, 1, s28
	v_lshlrev_b32_e32 v197, 1, v157
	v_add3_u32 v187, v134, v185, v197
	ds_read_b64_tr_b16 v[226:227], v187 offset:35904
	ds_read_b64_tr_b16 v[224:225], v187 offset:34816
	ds_read_b64_tr_b16 v[230:231], v187 offset:44608
	ds_read_b64_tr_b16 v[234:235], v187 offset:35936
	ds_read_b64_tr_b16 v[232:233], v187 offset:34848
	ds_read_b64_tr_b16 v[238:239], v187 offset:44640
	v_add3_u32 v193, v134, v186, v197
	ds_read_b64_tr_b16 v[228:229], v193 offset:34816
	ds_read_b64_tr_b16 v[236:237], v193 offset:34848
	v_mul_f32_e32 v98, v132, v98
	v_mul_f32_e32 v99, v132, v99
	v_mul_f32_e32 v96, v132, v96
	v_mul_f32_e32 v97, v132, v97
	v_mul_f32_e32 v102, v132, v102
	v_mul_f32_e32 v103, v132, v103
	v_mul_f32_e32 v100, v132, v100
	v_mul_f32_e32 v101, v132, v101
	s_waitcnt lgkmcnt(6)
	v_mfma_f32_16x16x32_bf16 v[96:99], v[224:227], v[108:111], v[96:99]
	s_ashr_i32 s41, s40, 31
	s_lshl_b64 s[4:5], s[40:41], 10
	s_waitcnt lgkmcnt(3)
	v_mfma_f32_16x16x32_bf16 v[100:103], v[232:235], v[108:111], v[100:103]
	s_bitcmp1_b32 s27, 0
	v_lshl_add_u64 v[108:109], v[126:127], 0, s[4:5]
	s_cselect_b32 s4, 0x10400, 0
	s_waitcnt lgkmcnt(1)
	v_mfma_f32_16x16x32_bf16 v[96:99], v[228:231], v[104:107], v[96:99]
	s_add_i32 s27, s57, s4
	v_cvt_pk_bf16_f32 v112, v112, v113
	v_cvt_pk_bf16_f32 v113, v114, v115
	s_waitcnt lgkmcnt(0)
	v_mfma_f32_16x16x32_bf16 v[100:103], v[236:239], v[104:107], v[100:103]
	global_store_dwordx2 v[108:109], v[112:113], off
	s_nop 1
	v_cvt_pk_bf16_f32 v104, v96, v97
	v_cvt_pk_bf16_f32 v105, v98, v99
	s_nop 2
	v_cvt_pk_bf16_f32 v106, v100, v101
	v_cvt_pk_bf16_f32 v107, v102, v103
	ds_write_b128 v156, v[104:107]
	v_lshl_add_u32 v104, v120, 1, s27
	s_waitcnt vmcnt(14)
	ds_write_b128 v104, v[28:31]
	s_waitcnt vmcnt(13)
	ds_write_b128 v104, v[32:35] offset:17408
	s_waitcnt vmcnt(12)
	ds_write_b128 v104, v[40:43] offset:34816
	v_lshl_add_u32 v104, v122, 1, s27
	s_waitcnt vmcnt(11)
	ds_write_b128 v104, v[48:51]
	s_waitcnt vmcnt(10)
	ds_write_b128 v104, v[52:55] offset:17408
	s_waitcnt vmcnt(9)
	ds_write_b128 v104, v[64:67] offset:34816
	v_add3_u32 v104, s27, v119, v116
	s_waitcnt vmcnt(3)
	ds_write_b128 v104, v[72:75] offset:52224
	s_waitcnt lgkmcnt(0)
	s_and_saveexec_b64 s[40:41], s[0:1]
	v_add3_u32 v104, s27, v161, v198
	ds_write_b128 v104, v[44:47] offset:61440
	s_or_b64 exec, exec, s[40:41]
	s_cmp_gt_u32 s26, 31
	v_readlane_b32 s12, v254, 56
	s_waitcnt lgkmcnt(0)
	s_barrier
	ds_read_b128 v[110:113], v117
	ds_read_b128 v[200:203], v117 offset:1024
	ds_read_b128 v[204:207], v117 offset:2048
	ds_read_b128 v[208:211], v117 offset:3072
	v_lshl_add_u32 v109, v121, 1, s27
	v_mov_b32_e32 v104, s21
	ds_read_b32 v108, v104 offset:4
	v_add_u32_e32 v132, v109, v162
	ds_read2_b64 v[224:227], v132 offset1:4
	ds_read2_b64 v[228:231], v132 offset0:8 offset1:12
	ds_read2_b64 v[236:239], v132 offset0:16 offset1:20
	ds_read2_b64 v[240:243], v132 offset0:24 offset1:28
	v_add_u32_e32 v109, v109, v158
	v_readlane_b32 s13, v254, 57
	s_cbranch_scc1 .LBB0_517
	v_add_co_u32_e32 v28, vcc, 0x13f5c000, v154
	s_nop 1
	v_addc_co_u32_e32 v29, vcc, 0, v155, vcc
	v_add_co_u32_e32 v32, vcc, 0x1515c000, v154
	s_nop 1
	v_addc_co_u32_e32 v33, vcc, 0, v155, vcc
	v_add_co_u32_e32 v40, vcc, 0x1635c000, v154
	global_load_dwordx4 v[28:31], v[28:29], off
	s_nop 0
	global_load_dwordx4 v[32:35], v[32:33], off
	v_addc_co_u32_e32 v41, vcc, 0, v155, vcc
	v_add_co_u32_e32 v48, vcc, 0x13f5c000, v152
	global_load_dwordx4 v[40:43], v[40:41], off
	s_nop 0
	v_addc_co_u32_e32 v49, vcc, 0, v153, vcc
	v_add_co_u32_e32 v52, vcc, 0x1515c000, v152
	s_nop 1
	v_addc_co_u32_e32 v53, vcc, 0, v153, vcc
	v_add_co_u32_e32 v64, vcc, 0x1635c000, v152
	global_load_dwordx4 v[48:51], v[48:49], off
	s_nop 0
	global_load_dwordx4 v[52:55], v[52:53], off
	v_addc_co_u32_e32 v65, vcc, 0, v153, vcc
	v_add_co_u32_e32 v72, vcc, 0x17554000, v150
	global_load_dwordx4 v[64:67], v[64:65], off
	s_nop 0
	v_addc_co_u32_e32 v73, vcc, 0, v151, vcc
	global_load_dwordx4 v[72:75], v[72:73], off
	s_and_saveexec_b64 s[40:41], s[0:1]
	s_cbranch_execz .LBB0_516
	v_lshl_add_u64 v[44:45], v[144:145], 0, s[44:45]
	v_add_co_u32_e32 v44, vcc, 0x12d5c000, v44
	s_nop 1
	v_addc_co_u32_e32 v45, vcc, 0, v45, vcc
	global_load_dwordx4 v[44:47], v[44:45], off nt

; DI float lo16(unsigned u) { return __uint_as_float(u << 16); }
; DI void gdn_scan_item(const P& p, int item, unsigned char* smem) {
;     ...
;     auto step = [&](GdnRegs& R, int c) {
;         storel(R, c & 1);
;         __syncthreads();
;         loadr(R, c + 3);
;         const bf16_t* sW = (const bf16_t*)(smem + (c & 1) * BUFB); const bf16_t* sQI = sW + 64 * 136; const bf16_t* sKO = sQI + 64 * 136; const bf16_t* sAT = sKO + 64 * 136; const bf16_t* sU = sAT + 64 * 72;
;         const float dec = sdec[c];
;         bf16x8 Bs[4];
; #pragma unroll
;         for (int ks = 0; ks < 4; ++ks) Bs[ks] = __builtin_bit_cast(bf16x8, sBS[(nt * 4 + ks) * 64 + lane]);
;         {
;             f32x4 acc = (f32x4){0.f, 0.f, 0.f, 0.f};
; #pragma unroll
;             for (int ks = 0; ks < 4; ++ks) { const bf16_t* r0 = sW + (16 * mt + l15) * 136 + 32 * ks + 4 * g; acc = mfma16(Bs[ks], ld4x2(r0, r0 + 16), acc); }
;             {
;                 const u32x2 uu = *(const u32x2*)(sU + (16 * mt + l15) * 40 + 16 * nt + 4 * g);
;                 u32x2 vv; vv.x = pk2(lo16(uu.x) - acc[0], hi16(uu.x) - acc[1]); vv.y = pk2(lo16(uu.y) - acc[2], hi16(uu.y) - acc[3]);
;                 *(u32x2*)(sVN + (16 * mt + l15) * 40 + 16 * nt + 4 * g) = vv;
;             }
;         }
;         __syncthreads();
;         bf16x8 Bv[2];
; #pragma unroll
;         for (int k2 = 0; k2 < 2; ++k2) Bv[k2] = tr2(sVN + (32 * k2 + 8 * g + q4) * 40 + 16 * nt + 4 * p4, sVN + (32 * k2 + 8 * g + 4 + q4) * 40 + 16 * nt + 4 * p4);
;         {
;             f32x4 acc = (f32x4){0.f, 0.f, 0.f, 0.f};
; #pragma unroll
;             for (int ks = 0; ks < 4; ++ks) { const bf16_t* r0 = sQI + (16 * mt + l15) * 136 + 32 * ks + 4 * g; acc = mfma16(Bs[ks], ld4x2(r0, r0 + 16), acc); }
; #pragma unroll
;             for (int k2 = 0; k2 < 2; ++k2) acc = mfma16(Bv[k2], ld8(sAT + (16 * mt + l15) * 72 + 32 * k2 + 8 * g), acc);
;             bf16_t* ob = OG + (size_t)prow(b, dir, 64 * c) * 512 + 128 * h + 32 * cq;
;             u32x2 ov; ov.x = pk2(acc[0], acc[1]); ov.y = pk2(acc[2], acc[3]);
;             *(u32x2*)(ob + sgn * ((16 * mt + l15) * 512) + 16 * nt + 4 * g) = ov;
;         }
; #pragma unroll
;         for (int j = 0; j < 2; ++j) {
;             const int dt = 2 * mt + j;
;             st[j] *= dec;
; #pragma unroll
;             for (int k2 = 0; k2 < 2; ++k2) {
.LBB0_517:
	s_waitcnt lgkmcnt(3)
	v_mfma_f32_16x16x32_bf16 v[104:107], v[110:113], v[224:227], 0
	v_add3_u32 v114, v109, v163, v162
	ds_read_b64 v[232:233], v114 offset:61440
	v_add_u32_e32 v109, v109, v159
	s_waitcnt lgkmcnt(3)
	v_mfma_f32_16x16x32_bf16 v[104:107], v[200:203], v[228:231], v[104:107]
	v_add3_u32 v109, v109, v160, v199
	s_waitcnt lgkmcnt(0)
	v_lshlrev_b32_e32 v134, 16, v232
	v_mfma_f32_16x16x32_bf16 v[104:107], v[204:207], v[236:239], v[104:107]
	v_and_b32_e32 v114, 0xffff0000, v232
	s_sub_i32 s4, s22, 64
	v_mfma_f32_16x16x32_bf16 v[104:107], v[208:211], v[240:243], v[104:107]
	s_add_i32 s5, s22, 0xfffffec0
	s_cmp_lt_u32 s26, 3
	s_movk_i32 s6, 0x8ff
	s_nop 4
	v_sub_f32_e32 v104, v134, v104
	v_sub_f32_e32 v105, v114, v105
	v_cvt_pk_bf16_f32 v104, v104, v105
	v_lshlrev_b32_e32 v105, 16, v233
	v_sub_f32_e32 v105, v105, v106
	v_and_b32_e32 v106, 0xffff0000, v233
	v_sub_f32_e32 v106, v106, v107
	v_cvt_pk_bf16_f32 v105, v105, v106
	v_add_u32_e32 v114, 0x4000, v132
	ds_write_b64 v123, v[104:105]
	s_waitcnt lgkmcnt(0)
	s_barrier
	ds_read_b64_tr_b16 v[224:225], v164
	ds_read_b64_tr_b16 v[226:227], v165
	ds_read_b64_tr_b16 v[228:229], v183
	ds_read_b64_tr_b16 v[230:231], v184
	ds_read2_b64 v[232:235], v114 offset0:128 offset1:132
	ds_read2_b64 v[236:239], v114 offset0:136 offset1:140
	ds_read2_b64 v[240:243], v114 offset0:144 offset1:148
	ds_read2_b64 v[244:247], v114 offset0:152 offset1:156
	ds_read_b128 v[248:251], v109 offset:52224
	s_waitcnt lgkmcnt(4)
	v_mfma_f32_16x16x32_bf16 v[110:113], v[110:113], v[232:235], 0
	ds_read_b128 v[232:235], v109 offset:52288
	s_cselect_b32 s6, 0xff, s6
	s_cselect_b32 s7, s4, s5
	s_waitcnt lgkmcnt(4)
	v_mfma_f32_16x16x32_bf16 v[110:113], v[200:203], v[236:239], v[110:113]
	s_cselect_b32 s8, s3, s2
	s_add_i32 s4, s6, s24
	s_waitcnt lgkmcnt(3)
	v_mfma_f32_16x16x32_bf16 v[110:113], v[204:207], v[240:243], v[110:113]
	s_add_i32 s6, s4, 0xfffff741
	s_and_b64 s[4:5], s[38:39], exec
	s_waitcnt lgkmcnt(2)
	v_mfma_f32_16x16x32_bf16 v[110:113], v[208:211], v[244:247], v[110:113]
	s_cselect_b32 s4, s7, s6
	s_add_i32 s4, s4, s8
	s_waitcnt lgkmcnt(1)
	v_mfma_f32_16x16x32_bf16 v[110:113], v[224:227], v[248:251], v[110:113]
	s_ashr_i32 s5, s4, 31
	s_lshl_b64 s[4:5], s[4:5], 10
	s_waitcnt lgkmcnt(0)
	v_mfma_f32_16x16x32_bf16 v[110:113], v[228:231], v[232:235], v[110:113]
	v_mul_f32_e64 v98, v98, v108
	v_mul_f32_e64 v99, v99, v108
	v_mul_f32_e32 v96, v108, v96
	v_mul_f32_e32 v97, v108, v97
	v_lshl_add_u32 v109, v125, 1, s27
	s_nop 3
	v_cvt_pk_bf16_f32 v110, v110, v111
	v_cvt_pk_bf16_f32 v111, v112, v113
	v_lshl_add_u64 v[112:113], v[126:127], 0, s[4:5]
	global_store_dwordx2 v[112:113], v[110:111], off
	v_add3_u32 v114, v109, v185, v197
	ds_read_b64_tr_b16 v[238:239], v114 offset:35904
	ds_read_b64_tr_b16 v[236:237], v114 offset:34816
	ds_read_b64_tr_b16 v[240:241], v114 offset:34848
	ds_read_b64_tr_b16 v[246:247], v114 offset:44608
	ds_read_b64_tr_b16 v[242:243], v114 offset:35936
	ds_read_b64_tr_b16 v[250:251], v114 offset:44640
	s_waitcnt lgkmcnt(4)
	v_mfma_f32_16x16x32_bf16 v[96:99], v[236:239], v[224:227], v[96:99]
	v_add3_u32 v109, v109, v186, v197
	ds_read_b64_tr_b16 v[244:245], v109 offset:34816
	ds_read_b64_tr_b16 v[248:249], v109 offset:34848
	v_mul_f32_e32 v102, v108, v102
	v_mul_f32_e32 v103, v108, v103
	v_mul_f32_e32 v100, v108, v100
	v_mul_f32_e32 v101, v108, v101
	s_waitcnt lgkmcnt(1)
	v_mfma_f32_16x16x32_bf16 v[96:99], v[244:247], v[228:231], v[96:99]
	v_mfma_f32_16x16x32_bf16 v[100:103], v[240:243], v[224:227], v[100:103]
	s_waitcnt lgkmcnt(0)
	v_mfma_f32_16x16x32_bf16 v[100:103], v[248:251], v[228:231], v[100:103]
	s_nop 3
	s_nop 0
	v_cvt_pk_bf16_f32 v104, v96, v97
	v_cvt_pk_bf16_f32 v105, v98, v99
	s_nop 1
	v_cvt_pk_bf16_f32 v106, v100, v101
	v_cvt_pk_bf16_f32 v107, v102, v103
	ds_write_b128 v156, v[104:107]
	s_waitcnt vmcnt(8)
	ds_write_b128 v190, v[56:59]
	s_waitcnt vmcnt(7)
	ds_write_b128 v190, v[60:63] offset:17408
	s_waitcnt vmcnt(6)
	ds_write_b128 v190, v[68:71] offset:34816
	s_waitcnt vmcnt(5)
	ds_write_b128 v192, v[76:79]
	s_waitcnt vmcnt(4)
	ds_write_b128 v192, v[80:83] offset:17408
	s_waitcnt vmcnt(3)
	ds_write_b128 v192, v[84:87] offset:34816
	s_waitcnt vmcnt(2)
	ds_write_b128 v194, v[92:95] offset:52224
	s_waitcnt lgkmcnt(0)
	s_and_saveexec_b64 s[40:41], s[0:1]
	ds_write_b128 v191, v[88:91] offset:61440
	s_or_b64 exec, exec, s[40:41]
	s_cmp_gt_u32 s26, 30
	s_waitcnt lgkmcnt(0)
	s_barrier
	ds_read_b128 v[112:115], v117
	ds_read_b128 v[248:251], v117 offset:1024
	ds_read_b128 v[198:201], v117 offset:2048
	ds_read_b128 v[202:205], v117 offset:3072
	ds_read2_b64 v[224:227], v188 offset1:4
	ds_read2_b64 v[228:231], v188 offset0:8 offset1:12
	ds_read2_b64 v[232:235], v188 offset0:16 offset1:20
	ds_read2_b64 v[236:239], v188 offset0:24 offset1:28
	ds_read_b64 v[240:241], v195 offset:61440
	v_mov_b32_e32 v104, s21
	ds_read_b32 v132, v104 offset:8
	s_cbranch_scc1 .LBB0_523
	v_add_co_u32_e32 v56, vcc, 0x13f60000, v154
	s_nop 1
	v_addc_co_u32_e32 v57, vcc, 0, v155, vcc
	v_add_co_u32_e32 v60, vcc, 0x15160000, v154
	s_nop 1
	v_addc_co_u32_e32 v61, vcc, 0, v155, vcc
	v_add_co_u32_e32 v68, vcc, 0x16360000, v154
	global_load_dwordx4 v[56:59], v[56:57], off
	s_nop 0
	global_load_dwordx4 v[60:63], v[60:61], off
	v_addc_co_u32_e32 v69, vcc, 0, v155, vcc
	v_add_co_u32_e32 v76, vcc, 0x13f60000, v152
	global_load_dwordx4 v[68:71], v[68:69], off
	s_nop 0
	v_addc_co_u32_e32 v77, vcc, 0, v153, vcc
	v_add_co_u32_e32 v80, vcc, 0x15160000, v152
	s_nop 1
	v_addc_co_u32_e32 v81, vcc, 0, v153, vcc
	v_add_co_u32_e32 v84, vcc, 0x16360000, v152
	global_load_dwordx4 v[76:79], v[76:77], off
	s_nop 0
	global_load_dwordx4 v[80:83], v[80:81], off
	v_addc_co_u32_e32 v85, vcc, 0, v153, vcc
	v_add_co_u32_e32 v92, vcc, 0x17556000, v150
	global_load_dwordx4 v[84:87], v[84:85], off
	s_nop 0
	v_addc_co_u32_e32 v93, vcc, 0, v151, vcc
	global_load_dwordx4 v[92:95], v[92:93], off
	s_and_saveexec_b64 s[40:41], s[0:1]
	s_cbranch_execz .LBB0_522
	v_lshl_add_u64 v[88:89], v[144:145], 0, s[44:45]
	v_add_co_u32_e32 v88, vcc, 0x12d60000, v88
	s_nop 1
	v_addc_co_u32_e32 v89, vcc, 0, v89, vcc
	global_load_dwordx4 v[88:91], v[88:89], off nt
